# stick-breaking K/V tiles staged to the wave's LDS through registers (coalesced global_load_dwordx4 + ds_write_b128, two tiles ahead) instead of LDS-DMA
# baseline (speedup 1.0000x reference)
; __device__ __forceinline__ int otid() { int t = threadIdx.x; asm volatile("" : "+v"(t)); return t; }
; __device__ __forceinline__ void sb_load(SbFrags& F, const bf16_t* Pm, const bf16_t* VT, size_t tok0, int kv0, int h, int r32, int hi) {
;     const bf16_t* krow = Pm + (tok0 + kv0 + r32) * PW + PC_SBK + h * 64;
; #pragma unroll
;     for (int s = 0; s < 4; ++s) F.kf[s] = *(const bf16x8*)(krow + 16 * s + 8 * hi);
; #pragma unroll
;     for (int s = 0; s < 2; ++s) {
;         const bf16_t* v0p = VT + (size_t)(h * 64 + r32) * VTLD + tok0 + kv0 + 16 * s + 4 * hi; const bf16_t* v1p = v0p + (size_t)32 * VTLD;
;         F.v[4 * s + 0] = *(const s16x4*)v0p; F.v[4 * s + 1] = *(const s16x4*)(v0p + 8); F.v[4 * s + 2] = *(const s16x4*)v1p; F.v[4 * s + 3] = *(const s16x4*)(v1p + 8);
;     }
; }
; template <bool DRY> __device__ __forceinline__ void sb_unit(int b, int h, int qi, bf16_t* Pm, const bf16_t* VT) {
;     const int lane = otid() & 63, r32 = lane & 31, hi = lane >> 5;
;     const size_t tok0 = (size_t)b * SEQ; const int q0 = qi * 32;
;     bf16_t* qrow = Pm + (tok0 + q0 + r32) * PW + PC_SBQ + h * 64;
;     bf16x8 qf[4];
; #pragma unroll
;     for (int s = 0; s < 4; ++s) qf[s] = *(const bf16x8*)(qrow + 16 * s + 8 * hi);
;     float R = 0.f; f32x16 o0 = {}, o1 = {};
;     SbFrags cur, nxt;
;     sb_load(cur, Pm, VT, tok0, qi * 32, h, r32, hi);
; #pragma unroll 1
;     ...
;         sb_load(nxt, Pm, VT, tok0, (kt > 0 ? kt - 1 : 0) * 32, h, r32, hi);
.LBB0_741:
	v_ashrrev_i32_e32 v4, 9, v3
	v_mov_b32_e32 v0, v234
	v_and_b32_e32 v100, 63, v3
	v_ashrrev_i32_e32 v5, 31, v4
	v_and_b32_e32 v15, 31, v0
	v_bfe_u32 v16, v0, 5, 1
	v_lshlrev_b64 v[0:1], 11, v[4:5]
	v_lshlrev_b32_e32 v17, 5, v100
	v_or3_b32 v8, v15, v17, v0
	v_mov_b64_e32 v[6:7], s[42:43]
	v_and_b32_e32 v14, 0x1c0, v3
	v_mad_u64_u32 v[6:7], s[4:5], v8, s24, v[6:7]
	v_mad_i32_i24 v7, v1, s24, v7
	v_lshlrev_b32_e32 v8, 1, v14
	v_mov_b32_e32 v9, v2
	v_lshl_add_u64 v[84:85], v[6:7], 0, v[8:9]
	v_lshlrev_b32_e32 v10, 4, v16
	v_mov_b32_e32 v11, v2
	v_lshl_add_u64 v[12:13], v[84:85], 0, v[10:11]
	global_load_dwordx4 v[52:55], v[12:13], off offset:1280
	global_load_dwordx4 v[56:59], v[12:13], off offset:1312
	global_load_dwordx4 v[60:63], v[12:13], off offset:1344
	global_load_dwordx4 v[64:67], v[12:13], off offset:1376
	v_or_b32_e32 v12, v15, v14
	v_mul_u32_u24_e32 v12, 0x8200, v12
	v_lshlrev_b32_e32 v12, 1, v12
	v_mov_b32_e32 v13, v2
	v_lshl_add_u64 v[12:13], s[38:39], 0, v[12:13]
	v_lshlrev_b64 v[4:5], 12, v[4:5]
	v_lshlrev_b32_e32 v6, 3, v16
	v_mov_b32_e32 v7, v2
	v_lshl_add_u64 v[4:5], v[12:13], 0, v[4:5]
	v_lshlrev_b32_e32 v12, 6, v100
	v_mov_b32_e32 v13, v2
	v_lshl_add_u64 v[12:13], v[4:5], 0, v[12:13]
	v_lshl_add_u64 v[88:89], v[4:5], 0, v[6:7]
	v_xor_b32_e32 v4, 32, v238
	v_add_u32_e32 v5, 64, v239
	v_cmp_lt_i32_e32 vcc, v4, v5
	v_lshlrev_b32_e32 v86, 2, v16
	v_and_b32_e32 v98, 63, v87
	v_cndmask_b32_e32 v4, v238, v4, vcc
	v_lshlrev_b32_e32 v101, 2, v4
	v_or_b32_e32 v4, 1, v86
	v_cmp_lt_u32_e64 s[46:47], v4, v15
	v_or_b32_e32 v4, 2, v86
	v_cmp_lt_u32_e64 s[48:49], v4, v15
	v_or_b32_e32 v4, 3, v86
	v_cmp_lt_u32_e64 s[50:51], v4, v15
	v_or_b32_e32 v4, 8, v86
	v_cmp_lt_u32_e64 s[52:53], v4, v15
	v_or_b32_e32 v4, 9, v86
	v_cmp_lt_u32_e64 s[54:55], v4, v15
	v_or_b32_e32 v4, 10, v86
	v_cmp_lt_u32_e64 s[56:57], v4, v15
	v_or_b32_e32 v4, 11, v86
	v_cmp_lt_u32_e64 s[58:59], v4, v15
	v_or_b32_e32 v4, 16, v86
	v_cmp_lt_u32_e64 s[60:61], v4, v15
	v_or_b32_e32 v4, 17, v86
	v_cmp_lt_u32_e64 s[62:63], v4, v15
	v_or_b32_e32 v4, 18, v86
	v_cmp_lt_u32_e64 s[64:65], v4, v15
	v_or_b32_e32 v4, 19, v86
	v_cmp_lt_u32_e64 s[66:67], v4, v15
	v_or_b32_e32 v4, 24, v86
	v_cmp_lt_u32_e64 s[68:69], v4, v15
	v_or_b32_e32 v4, 25, v86
	v_cmp_lt_u32_e64 s[70:71], v4, v15
	v_or_b32_e32 v4, 26, v86
	v_cmp_lt_u32_e64 s[72:73], v4, v15
	v_or_b32_e32 v4, 27, v86
	v_or_b32_e32 v0, v0, v15
	v_cmp_lt_u32_e64 s[74:75], v4, v15
	v_lshl_add_u64 v[4:5], s[42:43], 0, v[8:9]
	v_mov_b32_e32 v102, 0
	v_lshlrev_b32_e32 v99, 5, v98
	v_or_b32_e32 v90, v0, v17
	v_mov_b32_e32 v91, v1
	v_lshl_add_u64 v[94:95], v[12:13], 0, v[6:7]
	s_mov_b32 s28, 0
	v_cmp_eq_u32_e64 s[12:13], 0, v16
	v_cmp_lt_u32_e64 s[44:45], v86, v15
	v_lshl_add_u64 v[92:93], v[4:5], 0, v[10:11]
	s_mov_b64 s[34:35], 0
	v_mov_b32_e32 v4, 0
	v_mov_b32_e32 v5, v102
	v_mov_b32_e32 v6, v102
	v_mov_b32_e32 v7, v102
	v_mov_b32_e32 v8, v102
	v_mov_b32_e32 v9, v102
	v_mov_b32_e32 v10, v102
	v_mov_b32_e32 v11, v102
	v_mov_b32_e32 v12, v102
	v_mov_b32_e32 v13, v102
	v_mov_b32_e32 v14, v102
	v_mov_b32_e32 v15, v102
	v_mov_b32_e32 v16, v102
	v_mov_b32_e32 v17, v102
	v_mov_b32_e32 v18, v102
	v_mov_b32_e32 v19, v102
	v_mov_b32_e32 v20, 0
	v_mov_b32_e32 v21, v102
	v_mov_b32_e32 v22, v102
	v_mov_b32_e32 v23, v102
	v_mov_b32_e32 v24, v102
	v_mov_b32_e32 v25, v102
	v_mov_b32_e32 v26, v102
	v_mov_b32_e32 v27, v102
	v_mov_b32_e32 v28, v102
	v_mov_b32_e32 v29, v102
	v_mov_b32_e32 v30, v102
	v_mov_b32_e32 v31, v102
	v_mov_b32_e32 v32, v102
	v_mov_b32_e32 v33, v102
	v_mov_b32_e32 v34, v102
	v_mov_b32_e32 v35, v102
	v_readfirstlane_b32 s14, v234
	s_lshl_b32 s98, s14, 8
	v_and_b32_e32 v36, 63, v234
	v_lshrrev_b32_e32 v37, 3, v36
	v_and_b32_e32 v38, 7, v36
	v_xor_b32_e32 v38, v38, v37
	v_ashrrev_i32_e32 v40, 9, v3
	v_lshlrev_b32_e32 v40, 11, v40
	v_and_b32_e32 v41, 63, v3
	v_lshl_add_u32 v40, v41, 5, v40
	v_bfe_u32 v42, v3, 6, 3
	v_add_u32_e32 v39, v40, v37
	v_lshlrev_b32_e32 v44, 7, v42
	v_lshl_add_u32 v44, v38, 4, v44
	v_add_u32_e32 v44, 0x900, v44
	v_mov_b32_e32 v45, 0
	v_mov_b64_e32 v[172:173], s[42:43]
	v_mad_u64_u32 v[172:173], vcc, v39, s24, v[172:173]
	v_lshl_add_u64 v[172:173], v[172:173], 0, v[44:45]
	v_mov_b32_e32 v46, 0xea00
	v_mov_b32_e32 v47, 0
	v_lshl_add_u64 v[174:175], v[172:173], 0, v[46:47]
	v_lshl_add_u64 v[176:177], v[174:175], 0, v[46:47]
	v_lshl_add_u64 v[178:179], v[176:177], 0, v[46:47]
	v_lshrrev_b32_e32 v37, 2, v36
	v_and_b32_e32 v38, 3, v36
	v_bfe_u32 v49, v36, 4, 2
	v_xor_b32_e32 v38, v38, v49
	v_lshl_add_u32 v39, v42, 6, v37
	v_lshlrev_b32_e32 v44, 1, v40
	v_lshl_add_u32 v44, v38, 4, v44
	v_mov_b64_e32 v[180:181], s[38:39]
	v_mov_b32_e32 v49, 0x10400
	v_mad_u64_u32 v[180:181], vcc, v39, v49, v[180:181]
	v_lshl_add_u64 v[180:181], v[180:181], 0, v[44:45]
	v_mov_b32_e32 v46, 0x104000
	v_lshl_add_u64 v[182:183], v[180:181], 0, v[46:47]
	v_lshl_add_u64 v[184:185], v[182:183], 0, v[46:47]
	v_lshl_add_u64 v[186:187], v[184:185], 0, v[46:47]
	v_mov_b32_e32 v188, 0xfffc5800
	v_mov_b32_e32 v189, -1
	v_mov_b32_e32 v190, 0xffffffc0
	v_mov_b32_e32 v191, -1
	v_and_b32_e32 v37, 31, v234
	v_bfe_u32 v38, v234, 5, 1
	v_and_b32_e32 v39, 7, v37
	v_lshlrev_b32_e32 v44, 7, v37
	v_add_u32_e32 v49, 0, v38
	v_xor_b32_e32 v49, v49, v39
	v_lshl_add_u32 v192, v49, 4, v44
	v_add_u32_e32 v49, 2, v38
	v_xor_b32_e32 v49, v49, v39
	v_lshl_add_u32 v193, v49, 4, v44
	v_add_u32_e32 v49, 4, v38
	v_xor_b32_e32 v49, v49, v39
	v_lshl_add_u32 v194, v49, 4, v44
	v_add_u32_e32 v49, 6, v38
	v_xor_b32_e32 v49, v49, v39
	v_lshl_add_u32 v195, v49, 4, v44
	v_bfe_u32 v39, v37, 2, 2
	v_lshlrev_b32_e32 v44, 6, v37
	v_lshl_add_u32 v44, v38, 3, v44
	v_xor_b32_e32 v49, 0, v39
	v_lshl_add_u32 v196, v49, 4, v44
	v_xor_b32_e32 v49, 1, v39
	v_lshl_add_u32 v197, v49, 4, v44
	v_xor_b32_e32 v49, 2, v39
	v_lshl_add_u32 v198, v49, 4, v44
	v_xor_b32_e32 v49, 3, v39
	v_lshl_add_u32 v199, v49, 4, v44
	global_load_dwordx4 v[140:143], v[172:173], off
	global_load_dwordx4 v[144:147], v[174:175], off
	global_load_dwordx4 v[148:151], v[176:177], off
	global_load_dwordx4 v[152:155], v[178:179], off
	global_load_dwordx4 v[156:159], v[180:181], off
	global_load_dwordx4 v[160:163], v[182:183], off
	global_load_dwordx4 v[164:167], v[184:185], off
	global_load_dwordx4 v[168:171], v[186:187], off
	v_cmp_lt_i32_e32 vcc, 0, v100
	v_add_u32_e32 v100, -1, v100
	s_nop 0
	s_cbranch_vccz .Lsb_nostep_a
	v_lshl_add_u64 v[172:173], v[172:173], 0, v[188:189]
	v_lshl_add_u64 v[174:175], v[174:175], 0, v[188:189]
	v_lshl_add_u64 v[176:177], v[176:177], 0, v[188:189]
	v_lshl_add_u64 v[178:179], v[178:179], 0, v[188:189]
	v_lshl_add_u64 v[180:181], v[180:181], 0, v[190:191]
	v_lshl_add_u64 v[182:183], v[182:183], 0, v[190:191]
	v_lshl_add_u64 v[184:185], v[184:185], 0, v[190:191]
	v_lshl_add_u64 v[186:187], v[186:187], 0, v[190:191]
; __device__ __forceinline__ int crow(int r, int hi) { return (r & 3) + 8 * (r >> 2) + 4 * hi; }
; __device__ __forceinline__ void sb_load(SbFrags& F, const bf16_t* Pm, const bf16_t* VT, size_t tok0, int kv0, int h, int r32, int hi) {
;     const bf16_t* krow = Pm + (tok0 + kv0 + r32) * PW + PC_SBK + h * 64;
; #pragma unroll
;     for (int s = 0; s < 4; ++s) F.kf[s] = *(const bf16x8*)(krow + 16 * s + 8 * hi);
; #pragma unroll
;     for (int s = 0; s < 2; ++s) {
;         const bf16_t* v0p = VT + (size_t)(h * 64 + r32) * VTLD + tok0 + kv0 + 16 * s + 4 * hi; const bf16_t* v1p = v0p + (size_t)32 * VTLD;
;         F.v[4 * s + 0] = *(const s16x4*)v0p; F.v[4 * s + 1] = *(const s16x4*)(v0p + 8); F.v[4 * s + 2] = *(const s16x4*)v1p; F.v[4 * s + 3] = *(const s16x4*)(v1p + 8);
;     }
; template <bool DRY> __device__ __forceinline__ void sb_unit(int b, int h, int qi, bf16_t* Pm, const bf16_t* VT) {
;     ...
;         sb_load(nxt, Pm, VT, tok0, (kt > 0 ? kt - 1 : 0) * 32, h, r32, hi);
;         f32x16 p = {};
; #pragma unroll
;         for (int s = 0; s < 4; ++s) p = __builtin_amdgcn_mfma_f32_32x32x16_bf16(cur.kf[s], qf[s], p, 0, 0, 0);
;         const bool diag = (kt == qi);
;         float lk[16], inner[16], Tg[4], TP[4], pre[4];
; #pragma unroll
;         for (int r = 0; r < 16; ++r) {
;             const float z = p[r] * 0.125f; p[r] = z;
;             const float e = __expf(-fabsf(z)); const float sp = fmaxf(z, 0.f) + __logf(1.f + e);
;             const bool valid = !diag || (crow(r, hi) < r32);
;             lk[r] = valid ? -sp : 0.f;
;         }
.Lsb_nostep_a:
	v_and_b32_e32 v218, 63, v234
	v_lshlrev_b32_e32 v218, 4, v218
	s_waitcnt vmcnt(0)
	v_add_u32_e32 v219, s98, v218
	ds_write_b128 v219, v[140:143]
	ds_write_b128 v219, v[144:147] offset:1024
	ds_write_b128 v219, v[148:151] offset:2048
	ds_write_b128 v219, v[152:155] offset:3072
	ds_write_b128 v219, v[156:159] offset:4096
	ds_write_b128 v219, v[160:163] offset:5120
	ds_write_b128 v219, v[164:167] offset:6144
	ds_write_b128 v219, v[168:171] offset:7168
	global_load_dwordx4 v[140:143], v[172:173], off
	global_load_dwordx4 v[144:147], v[174:175], off
	global_load_dwordx4 v[148:151], v[176:177], off
	global_load_dwordx4 v[152:155], v[178:179], off
	global_load_dwordx4 v[156:159], v[180:181], off
	global_load_dwordx4 v[160:163], v[182:183], off
	global_load_dwordx4 v[164:167], v[184:185], off
	global_load_dwordx4 v[168:171], v[186:187], off
	v_cmp_lt_i32_e32 vcc, 0, v100
	v_add_u32_e32 v100, -1, v100
	s_nop 0
	s_cbranch_vccz .Lsb_nostep_a2
	v_lshl_add_u64 v[172:173], v[172:173], 0, v[188:189]
	v_lshl_add_u64 v[174:175], v[174:175], 0, v[188:189]
	v_lshl_add_u64 v[176:177], v[176:177], 0, v[188:189]
	v_lshl_add_u64 v[178:179], v[178:179], 0, v[188:189]
	v_lshl_add_u64 v[180:181], v[180:181], 0, v[190:191]
	v_lshl_add_u64 v[182:183], v[182:183], 0, v[190:191]
	v_lshl_add_u64 v[184:185], v[184:185], 0, v[190:191]
	v_lshl_add_u64 v[186:187], v[186:187], 0, v[190:191]
.Lsb_nostep_a2:
.LBB0_742:
	s_xor_b32 s98, s98, 0x2000
	s_waitcnt vmcnt(0)
	v_add_u32_e32 v219, s98, v218
	ds_write_b128 v219, v[140:143]
	ds_write_b128 v219, v[144:147] offset:1024
	ds_write_b128 v219, v[148:151] offset:2048
	ds_write_b128 v219, v[152:155] offset:3072
	ds_write_b128 v219, v[156:159] offset:4096
	ds_write_b128 v219, v[160:163] offset:5120
	ds_write_b128 v219, v[164:167] offset:6144
	ds_write_b128 v219, v[168:171] offset:7168
	global_load_dwordx4 v[140:143], v[172:173], off
	global_load_dwordx4 v[144:147], v[174:175], off
	global_load_dwordx4 v[148:151], v[176:177], off
	global_load_dwordx4 v[152:155], v[178:179], off
	global_load_dwordx4 v[156:159], v[180:181], off
	global_load_dwordx4 v[160:163], v[182:183], off
	global_load_dwordx4 v[164:167], v[184:185], off
	global_load_dwordx4 v[168:171], v[186:187], off
	v_cmp_lt_i32_e32 vcc, 0, v100
	v_add_u32_e32 v100, -1, v100
	s_nop 0
	s_cbranch_vccz .Lsb_nostep_b
	v_lshl_add_u64 v[172:173], v[172:173], 0, v[188:189]
	v_lshl_add_u64 v[174:175], v[174:175], 0, v[188:189]
	v_lshl_add_u64 v[176:177], v[176:177], 0, v[188:189]
	v_lshl_add_u64 v[178:179], v[178:179], 0, v[188:189]
	v_lshl_add_u64 v[180:181], v[180:181], 0, v[190:191]
	v_lshl_add_u64 v[182:183], v[182:183], 0, v[190:191]
	v_lshl_add_u64 v[184:185], v[184:185], 0, v[190:191]
	v_lshl_add_u64 v[186:187], v[186:187], 0, v[190:191]
.Lsb_nostep_b:
	s_xor_b32 s99, s98, 0x2000
	v_add_u32_e32 v210, s99, v192
	v_add_u32_e32 v211, s99, v193
	v_add_u32_e32 v212, s99, v194
	v_add_u32_e32 v213, s99, v195
	v_add_u32_e32 v214, s99, v196
	v_add_u32_e32 v215, s99, v197
	v_add_u32_e32 v216, s99, v198
	v_add_u32_e32 v217, s99, v199
	ds_read_b128 v[136:139], v210
	ds_read_b128 v[112:115], v211
	ds_read_b128 v[108:111], v212
	ds_read_b128 v[104:107], v213
	ds_read_b64 v[80:81], v214 offset:4096
	ds_read_b64 v[82:83], v215 offset:4096
	ds_read_b64 v[72:73], v216 offset:4096
	ds_read_b64 v[74:75], v217 offset:4096
	ds_read_b64 v[76:77], v214 offset:6144
	ds_read_b64 v[78:79], v215 offset:6144
	ds_read_b64 v[68:69], v216 offset:6144
	ds_read_b64 v[70:71], v217 offset:6144
	s_waitcnt lgkmcnt(8)
	v_mfma_f32_32x32x16_bf16 v[36:51], v[136:139], v[52:55], 0
	v_mfma_f32_32x32x16_bf16 v[36:51], v[112:115], v[56:59], v[36:51]
	v_mfma_f32_32x32x16_bf16 v[36:51], v[108:111], v[60:63], v[36:51]
	v_mfma_f32_32x32x16_bf16 v[36:51], v[104:107], v[64:67], v[36:51]
	s_nop 11
	v_mul_f32_e32 v36, 0x3e38aa3b, v36
	v_mul_f32_e32 v37, 0x3e38aa3b, v37
	v_exp_f32_e64 v96, -|v36|
	v_exp_f32_e64 v97, -|v37|
	v_min_f32_e64 v104, -v36, 0
	v_min_f32_e64 v105, -v37, 0
	v_add_f32_e32 v96, 1.0, v96
	v_add_f32_e32 v97, 1.0, v97
	v_log_f32_e32 v96, v96
	v_log_f32_e32 v97, v97
	v_cndmask_b32_e64 v121, v102, 0, s[12:13]
	v_sub_f32_e32 v104, v104, v96
	v_sub_f32_e32 v105, v105, v97
	v_cndmask_b32_e64 v104, 0, v104, s[44:45]
	v_cndmask_b32_e64 v105, 0, v105, s[46:47]
	v_mul_f32_e32 v38, 0x3e38aa3b, v38
	v_mul_f32_e32 v39, 0x3e38aa3b, v39
	v_exp_f32_e64 v103, -|v38|
	v_exp_f32_e64 v120, -|v39|
	v_min_f32_e64 v106, -v38, 0
	v_min_f32_e64 v107, -v39, 0
	v_add_f32_e32 v103, 1.0, v103
	v_add_f32_e32 v120, 1.0, v120
	v_log_f32_e32 v103, v103
	v_log_f32_e32 v120, v120
	v_sub_f32_e32 v106, v106, v103
	v_sub_f32_e32 v107, v107, v120
	v_cndmask_b32_e64 v106, 0, v106, s[48:49]
	v_cndmask_b32_e64 v107, 0, v107, s[50:51]
	v_mul_f32_e32 v40, 0x3e38aa3b, v40
	v_mul_f32_e32 v41, 0x3e38aa3b, v41
	v_exp_f32_e64 v96, -|v40|
	v_exp_f32_e64 v97, -|v41|
	v_min_f32_e64 v108, -v40, 0
	v_min_f32_e64 v109, -v41, 0
	v_add_f32_e32 v96, 1.0, v96
	v_add_f32_e32 v97, 1.0, v97
	v_log_f32_e32 v96, v96
	v_log_f32_e32 v97, v97
	v_sub_f32_e32 v108, v108, v96
	v_sub_f32_e32 v109, v109, v97
	v_cndmask_b32_e64 v108, 0, v108, s[52:53]
	v_cndmask_b32_e64 v109, 0, v109, s[54:55]
	v_mul_f32_e32 v42, 0x3e38aa3b, v42
	v_mul_f32_e32 v43, 0x3e38aa3b, v43
	v_exp_f32_e64 v103, -|v42|
	v_exp_f32_e64 v120, -|v43|
	v_min_f32_e64 v110, -v42, 0
	v_min_f32_e64 v111, -v43, 0
	v_add_f32_e32 v103, 1.0, v103
	v_add_f32_e32 v120, 1.0, v120
	v_log_f32_e32 v103, v103
	v_log_f32_e32 v120, v120
	v_sub_f32_e32 v110, v110, v103
	v_sub_f32_e32 v111, v111, v120
	v_cndmask_b32_e64 v110, 0, v110, s[56:57]
	v_cndmask_b32_e64 v111, 0, v111, s[58:59]
	v_mul_f32_e32 v44, 0x3e38aa3b, v44
; __device__ __forceinline__ unsigned cvtpk(float lo, float hi) { f32x2_t v = {lo, hi}; bf16x2_t b = __builtin_convertvector(v, bf16x2_t); return __builtin_bit_cast(unsigned, b); }
; __device__ __forceinline__ int crow(int r, int hi) { return (r & 3) + 8 * (r >> 2) + 4 * hi; }
; template <bool DRY> __device__ __forceinline__ void sb_unit(int b, int h, int qi, bf16_t* Pm, const bf16_t* VT) {
;     ...
;             const float z = p[r] * 0.125f; p[r] = z;
;             const float e = __expf(-fabsf(z)); const float sp = fmaxf(z, 0.f) + __logf(1.f + e);
;             const bool valid = !diag || (crow(r, hi) < r32);
;             lk[r] = valid ? -sp : 0.f;
;         }
; #pragma unroll
;         for (int g = 0; g < 4; ++g) {
;             const float s3 = lk[4 * g + 3], s2 = s3 + lk[4 * g + 2], s1 = s2 + lk[4 * g + 1];
;             inner[4 * g + 3] = 0.f; inner[4 * g + 2] = s3; inner[4 * g + 1] = s2; inner[4 * g] = s1; Tg[g] = s1 + lk[4 * g];
;             TP[g] = __shfl_xor(Tg[g], 32);
;         }
;         float run = 0.f;
; #pragma unroll
;         for (int g = 3; g >= 0; --g) { pre[g] = run + (hi == 0 ? TP[g] : 0.f); run += Tg[g] + TP[g]; }
; #pragma unroll
;         for (int r = 0; r < 16; ++r) {
;             const bool valid = !diag || (crow(r, hi) < r32);
;             const float ex = fminf(p[r] + lk[r] + R + pre[r >> 2] + inner[r], 0.f);
;             p[r] = valid ? __expf(ex) : 0.f;
;         }
;         R += run;
; #pragma unroll
;         for (int s = 0; s < 2; ++s) {
;             const u32x4 pw = (u32x4){cvtpk(p[8 * s + 0], p[8 * s + 1]), cvtpk(p[8 * s + 2], p[8 * s + 3]), cvtpk(p[8 * s + 4], p[8 * s + 5]), cvtpk(p[8 * s + 6], p[8 * s + 7])};
;             const bf16x8 pf = __builtin_bit_cast(bf16x8, pw);
;             const s16x4 l0 = cur.v[4 * s], h0 = cur.v[4 * s + 1], l1 = cur.v[4 * s + 2], h1 = cur.v[4 * s + 3];
;             const bf16x8 v0 = (bf16x8){l0[0], l0[1], l0[2], l0[3], h0[0], h0[1], h0[2], h0[3]};
;             const bf16x8 v1 = (bf16x8){l1[0], l1[1], l1[2], l1[3], h1[0], h1[1], h1[2], h1[3]};
;             o0 = __builtin_amdgcn_mfma_f32_32x32x16_bf16(v0, pf, o0, 0, 0, 0);
;             o1 = __builtin_amdgcn_mfma_f32_32x32x16_bf16(v1, pf, o1, 0, 0, 0);
;         }
;         if (__all(R < -104.f)) break;
	v_mul_f32_e32 v45, 0x3e38aa3b, v45
	v_exp_f32_e64 v96, -|v44|
	v_exp_f32_e64 v97, -|v45|
	v_min_f32_e64 v112, -v44, 0
	v_min_f32_e64 v113, -v45, 0
	v_add_f32_e32 v96, 1.0, v96
	v_add_f32_e32 v97, 1.0, v97
	v_log_f32_e32 v96, v96
	v_log_f32_e32 v97, v97
	v_sub_f32_e32 v112, v112, v96
	v_sub_f32_e32 v113, v113, v97
	v_cndmask_b32_e64 v112, 0, v112, s[60:61]
	v_cndmask_b32_e64 v113, 0, v113, s[62:63]
	v_mul_f32_e32 v46, 0x3e38aa3b, v46
	v_mul_f32_e32 v47, 0x3e38aa3b, v47
	v_exp_f32_e64 v103, -|v46|
	v_exp_f32_e64 v120, -|v47|
	v_min_f32_e64 v114, -v46, 0
	v_min_f32_e64 v115, -v47, 0
	v_add_f32_e32 v103, 1.0, v103
	v_add_f32_e32 v120, 1.0, v120
	v_log_f32_e32 v103, v103
	v_log_f32_e32 v120, v120
	v_sub_f32_e32 v114, v114, v103
	v_sub_f32_e32 v115, v115, v120
	v_cndmask_b32_e64 v114, 0, v114, s[64:65]
	v_cndmask_b32_e64 v115, 0, v115, s[66:67]
	v_mul_f32_e32 v48, 0x3e38aa3b, v48
	v_mul_f32_e32 v49, 0x3e38aa3b, v49
	v_exp_f32_e64 v96, -|v48|
	v_exp_f32_e64 v97, -|v49|
	v_min_f32_e64 v116, -v48, 0
	v_min_f32_e64 v117, -v49, 0
	v_add_f32_e32 v96, 1.0, v96
	v_add_f32_e32 v97, 1.0, v97
	v_log_f32_e32 v96, v96
	v_log_f32_e32 v97, v97
	v_sub_f32_e32 v116, v116, v96
	v_sub_f32_e32 v117, v117, v97
	v_cndmask_b32_e64 v116, 0, v116, s[68:69]
	v_cndmask_b32_e64 v117, 0, v117, s[70:71]
	v_mul_f32_e32 v50, 0x3e38aa3b, v50
	v_mul_f32_e32 v51, 0x3e38aa3b, v51
	v_exp_f32_e64 v103, -|v50|
	v_exp_f32_e64 v120, -|v51|
	v_min_f32_e64 v118, -v50, 0
	v_min_f32_e64 v119, -v51, 0
	v_add_f32_e32 v103, 1.0, v103
	v_add_f32_e32 v120, 1.0, v120
	v_log_f32_e32 v103, v103
	v_log_f32_e32 v120, v120
	v_sub_f32_e32 v118, v118, v103
	v_sub_f32_e32 v119, v119, v120
	v_cndmask_b32_e64 v118, 0, v118, s[72:73]
	v_cndmask_b32_e64 v119, 0, v119, s[74:75]
	v_add_f32_e32 v106, v106, v107
	v_add_f32_e32 v110, v110, v111
	v_add_f32_e32 v114, v114, v115
	v_add_f32_e32 v118, v118, v119
	v_add_f32_e32 v105, v105, v106
	v_add_f32_e32 v109, v109, v110
	v_add_f32_e32 v113, v113, v114
	v_add_f32_e32 v117, v117, v118
	v_add_f32_e32 v104, v104, v105
	v_add_f32_e32 v108, v108, v109
	v_add_f32_e32 v112, v112, v113
	v_add_f32_e32 v116, v116, v117
	v_add_f32_e32 v122, v116, v121
	v_add_f32_e32 v36, v36, v104
	v_add_f32_e32 v37, v37, v105
	v_add_f32_e32 v38, v38, v106
	v_add_f32_e32 v39, v39, v107
	v_add_f32_e32 v123, v122, v112
	v_add_f32_e32 v40, v40, v108
	v_add_f32_e32 v41, v41, v109
	v_add_f32_e32 v42, v42, v110
	v_add_f32_e32 v43, v43, v111
	v_add_f32_e32 v124, v123, v108
	v_add_f32_e32 v44, v44, v112
	v_add_f32_e32 v45, v45, v113
	v_add_f32_e32 v46, v46, v114
	v_add_f32_e32 v47, v47, v115
	v_add_f32_e32 v125, v124, v104
	v_add_f32_e32 v48, v48, v116
	v_add_f32_e32 v49, v49, v117
	v_add_f32_e32 v50, v50, v118
	v_add_f32_e32 v51, v51, v119
	v_mov_b32_e32 v126, v122
	v_cndmask_b32_e64 v130, v121, v125, s[12:13]
	v_cndmask_b32_e64 v127, v123, v122, s[12:13]
	v_cndmask_b32_e64 v128, v124, v123, s[12:13]
	v_cndmask_b32_e64 v129, v125, v124, s[12:13]
	v_permlane32_swap_b32_e32 v126, v130
	v_permlane32_swap_b32_e32 v127, v122
	v_permlane32_swap_b32_e32 v128, v123
	v_permlane32_swap_b32_e32 v129, v124
	v_add_f32_e32 v102, v125, v126
	v_add_f32_e32 v127, v127, v122
	v_add_f32_e32 v128, v128, v123
	v_add_f32_e32 v129, v129, v124
	v_add_f32_e32 v48, v48, v130
	v_add_f32_e32 v49, v49, v130
	v_add_f32_e32 v50, v50, v130
	v_add_f32_e32 v51, v51, v130
	v_add_f32_e32 v44, v44, v127
	v_add_f32_e32 v45, v45, v127
	v_add_f32_e32 v46, v46, v127
	v_add_f32_e32 v47, v47, v127
	v_add_f32_e32 v40, v40, v128
	v_add_f32_e32 v41, v41, v128
	v_add_f32_e32 v42, v42, v128
	v_add_f32_e32 v43, v43, v128
	v_add_f32_e32 v36, v36, v129
	v_add_f32_e32 v37, v37, v129
	v_add_f32_e32 v38, v38, v129
	v_add_f32_e32 v39, v39, v129
	v_exp_f32_e64 v36, v36 clamp
	v_exp_f32_e64 v37, v37 clamp
	v_exp_f32_e64 v38, v38 clamp
	v_exp_f32_e64 v39, v39 clamp
	v_exp_f32_e64 v40, v40 clamp
	v_exp_f32_e64 v41, v41 clamp
	v_exp_f32_e64 v42, v42 clamp
	v_exp_f32_e64 v43, v43 clamp
	v_exp_f32_e64 v44, v44 clamp
	v_exp_f32_e64 v45, v45 clamp
	v_exp_f32_e64 v46, v46 clamp
	v_exp_f32_e64 v47, v47 clamp
	v_exp_f32_e64 v48, v48 clamp
	v_exp_f32_e64 v49, v49 clamp
	v_exp_f32_e64 v50, v50 clamp
	v_exp_f32_e64 v51, v51 clamp
	s_nop 0
	v_cndmask_b32_e64 v36, 0, v36, s[44:45]
	v_cndmask_b32_e64 v37, 0, v37, s[46:47]
	v_cndmask_b32_e64 v38, 0, v38, s[48:49]
	v_cndmask_b32_e64 v39, 0, v39, s[50:51]
	v_cndmask_b32_e64 v40, 0, v40, s[52:53]
	v_cndmask_b32_e64 v41, 0, v41, s[54:55]
	v_cndmask_b32_e64 v42, 0, v42, s[56:57]
	v_cndmask_b32_e64 v43, 0, v43, s[58:59]
	v_cndmask_b32_e64 v44, 0, v44, s[60:61]
	v_cndmask_b32_e64 v45, 0, v45, s[62:63]
	v_cndmask_b32_e64 v46, 0, v46, s[64:65]
	v_cndmask_b32_e64 v47, 0, v47, s[66:67]
	v_cndmask_b32_e64 v48, 0, v48, s[68:69]
	v_cndmask_b32_e64 v49, 0, v49, s[70:71]
	v_cndmask_b32_e64 v50, 0, v50, s[72:73]
	v_cndmask_b32_e64 v51, 0, v51, s[74:75]
	v_cvt_pk_bf16_f32 v36, v36, v37
	v_cvt_pk_bf16_f32 v37, v38, v39
	v_cvt_pk_bf16_f32 v38, v40, v41
	v_cvt_pk_bf16_f32 v39, v42, v43
	s_mov_b32 s4, 0xc3160a50
	v_cmp_gt_f32_e32 vcc, s4, v102
	s_waitcnt lgkmcnt(0)
	v_mfma_f32_32x32x16_bf16 v[4:19], v[80:83], v[36:39], v[4:19]
	v_cvt_pk_bf16_f32 v44, v44, v45
	v_cvt_pk_bf16_f32 v45, v46, v47
	v_mfma_f32_32x32x16_bf16 v[20:35], v[76:79], v[36:39], v[20:35]
	v_cvt_pk_bf16_f32 v46, v48, v49
	v_cvt_pk_bf16_f32 v47, v50, v51
	s_cmp_eq_u32 vcc_hi, exec_hi
	s_cselect_b64 s[4:5], -1, 0
	v_cmp_eq_u32_e32 vcc, s28, v98
	s_or_b64 s[4:5], s[4:5], vcc
	s_add_i32 s28, s28, 1
	s_and_b64 s[4:5], exec, s[4:5]
	s_or_b64 s[34:35], s[4:5], s[34:35]
	v_mfma_f32_32x32x16_bf16 v[4:19], v[72:75], v[44:47], v[4:19]
	v_mfma_f32_32x32x16_bf16 v[20:35], v[68:71], v[44:47], v[20:35]
	s_andn2_b64 exec, exec, s[34:35]
	s_cbranch_execz .Lsbl_exit
; __device__ __forceinline__ int otid() { int t = threadIdx.x; asm volatile("" : "+v"(t)); return t; }
; __device__ __forceinline__ void sb_load(SbFrags& F, const bf16_t* Pm, const bf16_t* VT, size_t tok0, int kv0, int h, int r32, int hi) {
;     const bf16_t* krow = Pm + (tok0 + kv0 + r32) * PW + PC_SBK + h * 64;
; #pragma unroll
;     for (int s = 0; s < 4; ++s) F.kf[s] = *(const bf16x8*)(krow + 16 * s + 8 * hi);
; #pragma unroll
;     for (int s = 0; s < 2; ++s) {
;         const bf16_t* v0p = VT + (size_t)(h * 64 + r32) * VTLD + tok0 + kv0 + 16 * s + 4 * hi; const bf16_t* v1p = v0p + (size_t)32 * VTLD;
;         F.v[4 * s + 0] = *(const s16x4*)v0p; F.v[4 * s + 1] = *(const s16x4*)(v0p + 8); F.v[4 * s + 2] = *(const s16x4*)v1p; F.v[4 * s + 3] = *(const s16x4*)(v1p + 8);
;     }
; }
; template <bool DRY> __device__ __forceinline__ void sb_unit(int b, int h, int qi, bf16_t* Pm, const bf16_t* VT) {
;     const int lane = otid() & 63, r32 = lane & 31, hi = lane >> 5;
;     const size_t tok0 = (size_t)b * SEQ; const int q0 = qi * 32;
;     bf16_t* qrow = Pm + (tok0 + q0 + r32) * PW + PC_SBQ + h * 64;
;     bf16x8 qf[4];
; #pragma unroll
;     for (int s = 0; s < 4; ++s) qf[s] = *(const bf16x8*)(qrow + 16 * s + 8 * hi);
;     float R = 0.f; f32x16 o0 = {}, o1 = {};
;     SbFrags cur, nxt;
;     sb_load(cur, Pm, VT, tok0, qi * 32, h, r32, hi);
; #pragma unroll 1
;     ...
;         sb_load(nxt, Pm, VT, tok0, (kt > 0 ? kt - 1 : 0) * 32, h, r32, hi);
;         f32x16 p = {};
; #pragma unroll
;         for (int s = 0; s < 4; ++s) p = __builtin_amdgcn_mfma_f32_32x32x16_bf16(cur.kf[s], qf[s], p, 0, 0, 0);
.Lsbl_loop:
	s_xor_b32 s98, s98, 0x2000
	s_waitcnt vmcnt(0)
	v_add_u32_e32 v219, s98, v218
	ds_write_b128 v219, v[140:143]
	ds_write_b128 v219, v[144:147] offset:1024
	ds_write_b128 v219, v[148:151] offset:2048
	ds_write_b128 v219, v[152:155] offset:3072
	ds_write_b128 v219, v[156:159] offset:4096
	ds_write_b128 v219, v[160:163] offset:5120
	ds_write_b128 v219, v[164:167] offset:6144
	ds_write_b128 v219, v[168:171] offset:7168
	global_load_dwordx4 v[140:143], v[172:173], off
	global_load_dwordx4 v[144:147], v[174:175], off
	global_load_dwordx4 v[148:151], v[176:177], off
	global_load_dwordx4 v[152:155], v[178:179], off
	global_load_dwordx4 v[156:159], v[180:181], off
	global_load_dwordx4 v[160:163], v[182:183], off
	global_load_dwordx4 v[164:167], v[184:185], off
	global_load_dwordx4 v[168:171], v[186:187], off
	v_cmp_lt_i32_e32 vcc, 0, v100
	v_add_u32_e32 v100, -1, v100
	s_nop 0
	s_cbranch_vccz .Lsb_nostep_c
	v_lshl_add_u64 v[172:173], v[172:173], 0, v[188:189]
	v_lshl_add_u64 v[174:175], v[174:175], 0, v[188:189]
	v_lshl_add_u64 v[176:177], v[176:177], 0, v[188:189]
	v_lshl_add_u64 v[178:179], v[178:179], 0, v[188:189]
	v_lshl_add_u64 v[180:181], v[180:181], 0, v[190:191]
	v_lshl_add_u64 v[182:183], v[182:183], 0, v[190:191]
	v_lshl_add_u64 v[184:185], v[184:185], 0, v[190:191]
	v_lshl_add_u64 v[186:187], v[186:187], 0, v[190:191]
.Lsb_nostep_c:
	s_xor_b32 s99, s98, 0x2000
	v_add_u32_e32 v210, s99, v192
	v_add_u32_e32 v211, s99, v193
	v_add_u32_e32 v212, s99, v194
	v_add_u32_e32 v213, s99, v195
	v_add_u32_e32 v214, s99, v196
	v_add_u32_e32 v215, s99, v197
	v_add_u32_e32 v216, s99, v198
	v_add_u32_e32 v217, s99, v199
	ds_read_b128 v[136:139], v210
	ds_read_b128 v[112:115], v211
	ds_read_b128 v[108:111], v212
	ds_read_b128 v[104:107], v213
	ds_read_b64 v[80:81], v214 offset:4096
	ds_read_b64 v[82:83], v215 offset:4096
	ds_read_b64 v[72:73], v216 offset:4096
	ds_read_b64 v[74:75], v217 offset:4096
	ds_read_b64 v[76:77], v214 offset:6144
	ds_read_b64 v[78:79], v215 offset:6144
	ds_read_b64 v[68:69], v216 offset:6144
	ds_read_b64 v[70:71], v217 offset:6144
	s_waitcnt lgkmcnt(8)
; template <bool DRY> __device__ __forceinline__ void sb_unit(int b, int h, int qi, bf16_t* Pm, const bf16_t* VT) {
;     ...
;         sb_load(nxt, Pm, VT, tok0, (kt > 0 ? kt - 1 : 0) * 32, h, r32, hi);
;         f32x16 p = {};
; #pragma unroll
;         for (int s = 0; s < 4; ++s) p = __builtin_amdgcn_mfma_f32_32x32x16_bf16(cur.kf[s], qf[s], p, 0, 0, 0);
;         const bool diag = (kt == qi);
;         float lk[16], inner[16], Tg[4], TP[4], pre[4];
; #pragma unroll
;         for (int r = 0; r < 16; ++r) {
;             const float z = p[r] * 0.125f; p[r] = z;
;             const float e = __expf(-fabsf(z)); const float sp = fmaxf(z, 0.f) + __logf(1.f + e);
;             const bool valid = !diag || (crow(r, hi) < r32);
;             lk[r] = valid ? -sp : 0.f;
;         }
; #pragma unroll
;         for (int g = 0; g < 4; ++g) {
;             const float s3 = lk[4 * g + 3], s2 = s3 + lk[4 * g + 2], s1 = s2 + lk[4 * g + 1];
;             inner[4 * g + 3] = 0.f; inner[4 * g + 2] = s3; inner[4 * g + 1] = s2; inner[4 * g] = s1; Tg[g] = s1 + lk[4 * g];
;             TP[g] = __shfl_xor(Tg[g], 32);
;         }
;         float run = 0.f;
; #pragma unroll
;         for (int g = 3; g >= 0; --g) { pre[g] = run + (hi == 0 ? TP[g] : 0.f); run += Tg[g] + TP[g]; }
; #pragma unroll
;         for (int r = 0; r < 16; ++r) {
;             const bool valid = !diag || (crow(r, hi) < r32);
;             const float ex = fminf(p[r] + lk[r] + R + pre[r >> 2] + inner[r], 0.f);
;             p[r] = valid ? __expf(ex) : 0.f;
;         }
;         R += run;
; #pragma unroll
;         for (int s = 0; s < 2; ++s) {
;             const u32x4 pw = (u32x4){cvtpk(p[8 * s + 0], p[8 * s + 1]), cvtpk(p[8 * s + 2], p[8 * s + 3]), cvtpk(p[8 * s + 4], p[8 * s + 5]), cvtpk(p[8 * s + 6], p[8 * s + 7])};
;             const bf16x8 pf = __builtin_bit_cast(bf16x8, pw);
;             const s16x4 l0 = cur.v[4 * s], h0 = cur.v[4 * s + 1], l1 = cur.v[4 * s + 2], h1 = cur.v[4 * s + 3];
;             const bf16x8 v0 = (bf16x8){l0[0], l0[1], l0[2], l0[3], h0[0], h0[1], h0[2], h0[3]};
;             const bf16x8 v1 = (bf16x8){l1[0], l1[1], l1[2], l1[3], h1[0], h1[1], h1[2], h1[3]};
;             o0 = __builtin_amdgcn_mfma_f32_32x32x16_bf16(v0, pf, o0, 0, 0, 0);
;             o1 = __builtin_amdgcn_mfma_f32_32x32x16_bf16(v1, pf, o1, 0, 0, 0);
;         }
;         if (__all(R < -104.f)) break;
	v_mfma_f32_32x32x16_bf16 v[36:51], v[136:139], v[52:55], 0
	v_mfma_f32_32x32x16_bf16 v[36:51], v[112:115], v[56:59], v[36:51]
	v_mfma_f32_32x32x16_bf16 v[36:51], v[108:111], v[60:63], v[36:51]
	v_mfma_f32_32x32x16_bf16 v[36:51], v[104:107], v[64:67], v[36:51]
	s_nop 11
	v_mul_f32_e32 v36, 0x3e38aa3b, v36
	v_mul_f32_e32 v37, 0x3e38aa3b, v37
	v_exp_f32_e64 v96, -|v36|
	v_exp_f32_e64 v97, -|v37|
	v_min_f32_e64 v104, -v36, 0
	v_min_f32_e64 v105, -v37, 0
	v_add_f32_e32 v96, 1.0, v96
	v_add_f32_e32 v97, 1.0, v97
	v_log_f32_e32 v96, v96
	v_log_f32_e32 v97, v97
	v_cndmask_b32_e64 v121, v102, 0, s[12:13]
	v_sub_f32_e32 v104, v104, v96
	v_sub_f32_e32 v105, v105, v97
	v_mul_f32_e32 v38, 0x3e38aa3b, v38
	v_mul_f32_e32 v39, 0x3e38aa3b, v39
	v_exp_f32_e64 v103, -|v38|
	v_exp_f32_e64 v120, -|v39|
	v_min_f32_e64 v106, -v38, 0
	v_min_f32_e64 v107, -v39, 0
	v_add_f32_e32 v103, 1.0, v103
	v_add_f32_e32 v120, 1.0, v120
	v_log_f32_e32 v103, v103
	v_log_f32_e32 v120, v120
	v_sub_f32_e32 v106, v106, v103
	v_sub_f32_e32 v107, v107, v120
	v_mul_f32_e32 v40, 0x3e38aa3b, v40
	v_mul_f32_e32 v41, 0x3e38aa3b, v41
	v_exp_f32_e64 v96, -|v40|
	v_exp_f32_e64 v97, -|v41|
	v_min_f32_e64 v108, -v40, 0
	v_min_f32_e64 v109, -v41, 0
	v_add_f32_e32 v96, 1.0, v96
	v_add_f32_e32 v97, 1.0, v97
	v_log_f32_e32 v96, v96
	v_log_f32_e32 v97, v97
	v_sub_f32_e32 v108, v108, v96
	v_sub_f32_e32 v109, v109, v97
	v_mul_f32_e32 v42, 0x3e38aa3b, v42
	v_mul_f32_e32 v43, 0x3e38aa3b, v43
	v_exp_f32_e64 v103, -|v42|
	v_exp_f32_e64 v120, -|v43|
	v_min_f32_e64 v110, -v42, 0
	v_min_f32_e64 v111, -v43, 0
	v_add_f32_e32 v103, 1.0, v103
	v_add_f32_e32 v120, 1.0, v120
	v_log_f32_e32 v103, v103
	v_log_f32_e32 v120, v120
	v_sub_f32_e32 v110, v110, v103
	v_sub_f32_e32 v111, v111, v120
	v_mul_f32_e32 v44, 0x3e38aa3b, v44
	v_mul_f32_e32 v45, 0x3e38aa3b, v45
	v_exp_f32_e64 v96, -|v44|
	v_exp_f32_e64 v97, -|v45|
	v_min_f32_e64 v112, -v44, 0
	v_min_f32_e64 v113, -v45, 0
	v_add_f32_e32 v96, 1.0, v96
	v_add_f32_e32 v97, 1.0, v97
	v_log_f32_e32 v96, v96
	v_log_f32_e32 v97, v97
	v_sub_f32_e32 v112, v112, v96
	v_sub_f32_e32 v113, v113, v97
	v_mul_f32_e32 v46, 0x3e38aa3b, v46
	v_mul_f32_e32 v47, 0x3e38aa3b, v47
	v_exp_f32_e64 v103, -|v46|
	v_exp_f32_e64 v120, -|v47|
	v_min_f32_e64 v114, -v46, 0
	v_min_f32_e64 v115, -v47, 0
	v_add_f32_e32 v103, 1.0, v103
	v_add_f32_e32 v120, 1.0, v120
	v_log_f32_e32 v103, v103
	v_log_f32_e32 v120, v120
	v_sub_f32_e32 v114, v114, v103
	v_sub_f32_e32 v115, v115, v120
	v_mul_f32_e32 v48, 0x3e38aa3b, v48
	v_mul_f32_e32 v49, 0x3e38aa3b, v49
	v_exp_f32_e64 v96, -|v48|
	v_exp_f32_e64 v97, -|v49|
	v_min_f32_e64 v116, -v48, 0
	v_min_f32_e64 v117, -v49, 0
	v_add_f32_e32 v96, 1.0, v96
	v_add_f32_e32 v97, 1.0, v97
	v_log_f32_e32 v96, v96
	v_log_f32_e32 v97, v97
	v_sub_f32_e32 v116, v116, v96
	v_sub_f32_e32 v117, v117, v97
	v_mul_f32_e32 v50, 0x3e38aa3b, v50
	v_mul_f32_e32 v51, 0x3e38aa3b, v51
	v_exp_f32_e64 v103, -|v50|
	v_exp_f32_e64 v120, -|v51|
	v_min_f32_e64 v118, -v50, 0
	v_min_f32_e64 v119, -v51, 0
	v_add_f32_e32 v103, 1.0, v103
	v_add_f32_e32 v120, 1.0, v120
	v_log_f32_e32 v103, v103
	v_log_f32_e32 v120, v120
	v_sub_f32_e32 v118, v118, v103
	v_sub_f32_e32 v119, v119, v120
	v_add_f32_e32 v106, v106, v107
	v_add_f32_e32 v110, v110, v111
	v_add_f32_e32 v114, v114, v115
	v_add_f32_e32 v118, v118, v119
	v_add_f32_e32 v105, v105, v106
	v_add_f32_e32 v109, v109, v110
	v_add_f32_e32 v113, v113, v114
	v_add_f32_e32 v117, v117, v118
	v_add_f32_e32 v104, v104, v105
	v_add_f32_e32 v108, v108, v109
	v_add_f32_e32 v112, v112, v113
	v_add_f32_e32 v116, v116, v117
	v_add_f32_e32 v122, v116, v121
	v_add_f32_e32 v36, v36, v104
	v_add_f32_e32 v37, v37, v105
	v_add_f32_e32 v38, v38, v106
	v_add_f32_e32 v39, v39, v107
	v_add_f32_e32 v123, v122, v112
	v_add_f32_e32 v40, v40, v108
	v_add_f32_e32 v41, v41, v109
	v_add_f32_e32 v42, v42, v110
	v_add_f32_e32 v43, v43, v111
	v_add_f32_e32 v124, v123, v108
	v_add_f32_e32 v44, v44, v112
	v_add_f32_e32 v45, v45, v113
	v_add_f32_e32 v46, v46, v114
	v_add_f32_e32 v47, v47, v115
	v_add_f32_e32 v125, v124, v104
	v_add_f32_e32 v48, v48, v116
	v_add_f32_e32 v49, v49, v117
	v_add_f32_e32 v50, v50, v118
	v_add_f32_e32 v51, v51, v119
	v_mov_b32_e32 v126, v122
	v_cndmask_b32_e64 v130, v121, v125, s[12:13]
	v_cndmask_b32_e64 v127, v123, v122, s[12:13]
	v_cndmask_b32_e64 v128, v124, v123, s[12:13]
	v_cndmask_b32_e64 v129, v125, v124, s[12:13]
	v_permlane32_swap_b32_e32 v126, v130
	v_permlane32_swap_b32_e32 v127, v122
	v_permlane32_swap_b32_e32 v128, v123
	v_permlane32_swap_b32_e32 v129, v124
	v_add_f32_e32 v102, v125, v126
	v_add_f32_e32 v127, v127, v122
	v_add_f32_e32 v128, v128, v123
	v_add_f32_e32 v129, v129, v124
	v_add_f32_e32 v48, v48, v130
	v_add_f32_e32 v49, v49, v130
	v_add_f32_e32 v50, v50, v130
	v_add_f32_e32 v51, v51, v130
	v_add_f32_e32 v44, v44, v127
	v_add_f32_e32 v45, v45, v127
	v_add_f32_e32 v46, v46, v127
	v_add_f32_e32 v47, v47, v127
	v_add_f32_e32 v40, v40, v128
	v_add_f32_e32 v41, v41, v128
	v_add_f32_e32 v42, v42, v128
	v_add_f32_e32 v43, v43, v128
	v_add_f32_e32 v36, v36, v129
	v_add_f32_e32 v37, v37, v129
	v_add_f32_e32 v38, v38, v129
	v_add_f32_e32 v39, v39, v129
	v_exp_f32_e64 v36, v36 clamp
	v_exp_f32_e64 v37, v37 clamp
	v_exp_f32_e64 v38, v38 clamp
	v_exp_f32_e64 v39, v39 clamp
	v_exp_f32_e64 v40, v40 clamp
	v_exp_f32_e64 v41, v41 clamp
	v_exp_f32_e64 v42, v42 clamp
	v_exp_f32_e64 v43, v43 clamp
	v_exp_f32_e64 v44, v44 clamp
	v_exp_f32_e64 v45, v45 clamp
	v_exp_f32_e64 v46, v46 clamp
	v_exp_f32_e64 v47, v47 clamp
	v_exp_f32_e64 v48, v48 clamp
	v_exp_f32_e64 v49, v49 clamp
	v_exp_f32_e64 v50, v50 clamp
	v_exp_f32_e64 v51, v51 clamp
	s_nop 0
	v_cvt_pk_bf16_f32 v36, v36, v37
	v_cvt_pk_bf16_f32 v37, v38, v39
	v_cvt_pk_bf16_f32 v38, v40, v41
	v_cvt_pk_bf16_f32 v39, v42, v43
	s_mov_b32 s4, 0xc3160a50
	v_cmp_gt_f32_e32 vcc, s4, v102
	s_waitcnt lgkmcnt(0)
	v_mfma_f32_32x32x16_bf16 v[4:19], v[80:83], v[36:39], v[4:19]
	v_cvt_pk_bf16_f32 v44, v44, v45
	v_cvt_pk_bf16_f32 v45, v46, v47
	v_mfma_f32_32x32x16_bf16 v[20:35], v[76:79], v[36:39], v[20:35]
	v_cvt_pk_bf16_f32 v46, v48, v49
	v_cvt_pk_bf16_f32 v47, v50, v51
	s_cmp_eq_u32 vcc_hi, exec_hi
	s_cselect_b64 s[4:5], -1, 0
	v_cmp_eq_u32_e32 vcc, s28, v98
	s_or_b64 s[4:5], s[4:5], vcc
	s_add_i32 s28, s28, 1
	s_and_b64 s[4:5], exec, s[4:5]
	s_or_b64 s[34:35], s[4:5], s[34:35]
	v_mfma_f32_32x32x16_bf16 v[4:19], v[72:75], v[44:47], v[4:19]
	v_mfma_f32_32x32x16_bf16 v[20:35], v[68:71], v[44:47], v[20:35]
	s_andn2_b64 exec, exec, s[34:35]
	s_cbranch_execnz .Lsbl_loop
